# o16 + last 3072 w_in conversion items (LN1 fold incl.) deferred to GU1 idle workgroups via tail-mode re-entry of the prologue item loop
# speedup vs baseline: 1.0176x; 1.0011x over previous
_Z5k_fwd1P:
	s_load_dwordx8 s[80:87], s[0:1], 0xc0
	s_mov_b32 s96, 0
	v_cmp_gt_u32_e32 vcc, 4, v0
	v_writelane_b32 v253, s2, 0
	s_and_saveexec_b64 s[2:3], vcc
	v_lshl_add_u32 v1, v0, 2, 0
	v_add_u32_e32 v1, 0x27000, v1
	v_mov_b32_e32 v2, 0
	ds_write_b32 v1, v2
	s_or_b64 exec, exec, s[2:3]
	s_load_dwordx16 s[4:19], s[0:1], 0x40
	s_waitcnt lgkmcnt(0)
	s_barrier
	s_getreg_b32 s2, hwreg(HW_REG_XCC_ID, 0, 4)
	v_writelane_b32 v253, s4, 1
	s_and_b32 s2, s2, 15
	s_nop 0
	v_writelane_b32 v253, s5, 2
	v_writelane_b32 v253, s6, 3
	v_writelane_b32 v253, s7, 4
	v_writelane_b32 v253, s8, 5
	v_writelane_b32 v253, s9, 6
	v_writelane_b32 v253, s10, 7
	v_writelane_b32 v253, s11, 8
	v_writelane_b32 v253, s12, 9
	v_writelane_b32 v253, s13, 10
	v_writelane_b32 v253, s14, 11
	v_writelane_b32 v253, s15, 12
	v_writelane_b32 v253, s16, 13
	v_writelane_b32 v253, s17, 14
	v_writelane_b32 v253, s18, 15
	v_writelane_b32 v253, s19, 16
	v_writelane_b32 v253, s2, 17
	v_cmp_eq_u32_e64 s[4:5], 0, v0
	s_mov_b64 s[2:3], exec
	s_nop 0
	v_writelane_b32 v253, s4, 18
	s_nop 1
	v_writelane_b32 v253, s5, 19
	s_and_b64 s[4:5], s[2:3], s[4:5]
	s_mov_b64 exec, s[4:5]
	s_cbranch_execz .LBB0_5
	s_mov_b64 s[4:5], exec
	v_mbcnt_lo_u32_b32 v1, s4, 0
	v_mbcnt_hi_u32_b32 v1, s5, v1
	v_cmp_eq_u32_e32 vcc, 0, v1
	s_and_b64 s[6:7], exec, vcc
	s_mov_b64 exec, s[6:7]
	s_cbranch_execz .LBB0_5
	v_readlane_b32 s6, v253, 17
	s_lshl_b32 s6, s6, 8
	s_bcnt1_i32_b64 s4, s[4:5]
	v_mov_b32_e32 v1, s6
	v_mov_b32_e32 v2, s4
	global_atomic_add v1, v2, s[86:87] offset:1024

.Lpro_body:
	s_load_dwordx16 s[44:59], s[0:1], 0x40
	s_movk_i32 s2, 0x2100
	v_mul_lo_u32 v3, v2, s2
	v_and_b32_e32 v7, 7, v139
	v_lshrrev_b32_e32 v5, 3, v131
	v_add_u32_e32 v1, 0, v3
	v_mul_u32_u24_e32 v6, 0x420, v7
	v_lshlrev_b32_e32 v4, 2, v5
	v_add3_u32 v143, v1, v6, v4
	v_bfe_u32 v1, v139, 3, 1
	v_lshlrev_b32_e32 v6, 4, v131
	v_lshlrev_b32_e32 v8, 1, v131
	v_lshlrev_b32_e64 v153, v1, 1
	v_lshlrev_b32_e32 v1, 5, v1
	v_and_b32_e32 v6, 16, v6
	v_and_b32_e32 v8, 12, v8
	v_lshlrev_b32_e32 v138, 2, v133
	s_waitcnt lgkmcnt(0)
	s_cmp_lg_u64 s[50:51], 0
	v_or3_b32 v163, v1, v6, v8
	v_and_b32_e32 v1, 32, v138
	s_cselect_b64 s[26:27], -1, 0
	s_add_u32 s28, s86, 0x32000
	v_lshlrev_b32_e32 v134, 4, v7
	v_mov_b32_e32 v135, 0
	v_and_b32_e32 v140, 48, v139
	v_or3_b32 v166, v1, v6, v8
	v_lshlrev_b32_e32 v1, 2, v139
	v_and_b32_e32 v167, 7, v2
	s_addc_u32 s29, s87, 0
	v_lshl_add_u64 v[136:137], s[20:21], 0, v[134:135]
	v_and_b32_e32 v142, 60, v1
	v_or_b32_e32 v1, 0x200, v167
	v_and_b32_e32 v9, 1, v2
	v_lshlrev_b32_e32 v134, 2, v140
	s_add_u32 s30, s86, 0x43000
	v_lshlrev_b32_e32 v2, 3, v2
	v_readlane_b32 s4, v253, 0
	v_and_b32_e32 v141, 31, v139
	v_lshl_add_u64 v[144:145], s[50:51], 0, v[134:135]
	v_lshl_add_u64 v[146:147], s[52:53], 0, v[134:135]
	s_addc_u32 s31, s87, 0
	v_lshlrev_b32_e32 v134, 7, v1
	v_lshl_add_u32 v170, s4, 6, v2
	s_load_dword s4, s[0:1], 0xe0
	v_mov_b32_e32 v6, 0x1000
	v_lshlrev_b32_e32 v5, 11, v5
	v_lshl_add_u64 v[14:15], s[30:31], 0, v[134:135]
	v_lshlrev_b32_e32 v16, 2, v141
	v_mov_b32_e32 v17, v135
	v_lshrrev_b32_e32 v132, 5, v131
	v_lshl_or_b32 v168, v167, 5, v6
	v_lshl_or_b32 v6, v1, 16, v5
	v_lshl_add_u64 v[148:149], v[14:15], 0, v[16:17]
	v_lshl_add_u64 v[14:15], s[28:29], 0, v[134:135]
	v_mov_b32_e32 v5, v135
	v_lshl_add_u64 v[150:151], v[14:15], 0, v[4:5]
	v_mul_u32_u24_e32 v4, 0x84, v132
	s_movk_i32 s2, 0x201
	v_or_b32_e32 v8, 0x4000, v6
	v_or_b32_e32 v10, 0x8000, v6
	v_or_b32_e32 v12, 0xc000, v6
	v_or_b32_e32 v3, v3, v4
	v_cmp_lt_u32_e64 s[2:3], s2, v1
	v_mov_b32_e32 v1, v135
	v_add3_u32 v169, v3, v16, 0
	v_mul_u32_u24_e32 v152, 0x4070, v132
	s_waitcnt lgkmcnt(0)
	s_lshl_b32 s33, s4, 6
	s_cmp_eq_u32 s96, 0
	s_cbranch_scc1 .Lpro_t0
	s_lshl_b32 s33, s42, 3
	v_lshlrev_b32_e32 v170, 3, v130
.Lpro_t0:
	v_or_b32_e32 v171, 0xfffdf800, v132
	v_lshlrev_b32_e32 v154, 1, v6
	v_lshlrev_b32_e32 v156, 1, v8
	v_lshlrev_b32_e32 v158, 1, v10
	v_lshlrev_b32_e32 v160, 1, v12
	s_mov_b32 s46, 0x10000
	s_movk_i32 s47, 0x2000
	s_mov_b32 s69, 0x16000
	s_movk_i32 s70, 0x5000
	s_movk_i32 s71, 0xb0
	s_movk_i32 s72, 0xff80
	s_movk_i32 s73, 0x5800
	s_mov_b32 s74, 0xb000
	v_mbcnt_hi_u32_b32 v172, -1, v202
	v_mov_b32_e32 v173, 63
	v_mov_b32_e32 v174, 6
	v_mov_b32_e32 v175, 39
	v_mov_b32_e32 v176, v130
	s_mov_b32 s75, 0x1b000
	s_mov_b32 s76, 0x21000
	s_mov_b32 s77, 0x26000
	s_mov_b32 s78, 0x2c000
	s_mov_b32 s79, 0x31000
	s_mov_b32 s88, 0x37000
	s_mov_b32 s89, 0x3c000
	s_mov_b32 s90, 0x42000
	s_mov_b32 s91, 0x47000
	s_mov_b32 s92, 0x4d000
	s_mov_b32 s64, 0x52000
	s_movk_i32 s65, 0x41ff
	s_cmp_lg_u32 s96, 0
	s_cbranch_scc1 .Lpro_t1
	s_movk_i32 s65, 0x35ff
.Lpro_t1:
	v_cmp_gt_u32_e64 s[4:5], 16, v141
	v_cmp_gt_u32_e64 s[6:7], 32, v131
	v_cmp_eq_u32_e64 s[8:9], 0, v7
	v_cmp_gt_u32_e64 s[10:11], 16, v131
	v_cmp_eq_u32_e64 s[12:13], 1, v9
	s_mov_b64 s[34:35], 0
	s_mov_b32 s68, s42
	s_branch .LBB0_8

.LBB0_115:
	s_or_b64 exec, exec, s[24:25]
	s_cmp_lg_u32 s96, 0
	s_cbranch_scc1 .Lpro_ret
	s_load_dwordx16 s[44:59], s[0:1], 0x0
	s_waitcnt lgkmcnt(0)
	v_writelane_b32 v253, s44, 24
	s_nop 1
	v_writelane_b32 v253, s45, 25
	v_writelane_b32 v253, s46, 26
	v_writelane_b32 v253, s47, 27
	v_writelane_b32 v253, s48, 28
	v_writelane_b32 v253, s49, 29
	v_writelane_b32 v253, s50, 30
	v_writelane_b32 v253, s51, 31
	v_writelane_b32 v253, s52, 32
	v_writelane_b32 v253, s53, 33
	v_writelane_b32 v253, s54, 34
	v_writelane_b32 v253, s55, 35
	v_writelane_b32 v253, s56, 36
	v_writelane_b32 v253, s57, 37
	v_writelane_b32 v253, s58, 38
	v_writelane_b32 v253, s59, 39
	s_load_dwordx16 s[44:59], s[0:1], 0x80
	s_movk_i32 s0, 0x2008
	v_cmp_gt_i32_e32 vcc, s0, v130
	s_waitcnt lgkmcnt(0)
	v_writelane_b32 v253, s44, 40
	s_nop 1
	v_writelane_b32 v253, s45, 41
	v_writelane_b32 v253, s46, 42
	v_writelane_b32 v253, s47, 43
	v_writelane_b32 v253, s48, 44
	v_writelane_b32 v253, s49, 45
	v_writelane_b32 v253, s50, 46
	v_writelane_b32 v253, s51, 47
	v_writelane_b32 v253, s52, 48
	v_writelane_b32 v253, s53, 49
	v_writelane_b32 v253, s54, 50
	v_writelane_b32 v253, s55, 51
	v_writelane_b32 v253, s56, 52
	v_writelane_b32 v253, s57, 53
	v_writelane_b32 v253, s58, 54
	v_writelane_b32 v253, s59, 55
	s_and_saveexec_b64 s[0:1], vcc
	s_cbranch_execz .LBB0_120
	v_lshlrev_b32_e32 v8, 2, v131
	v_mov_b32_e32 v3, 0
	v_lshlrev_b32_e32 v2, 3, v131
	v_ashrrev_i32_e32 v131, 31, v130
	v_readlane_b32 s44, v253, 24
	v_lshl_add_u64 v[4:5], s[86:87], 0, v[2:3]
	s_mov_b64 s[2:3], 0xce60200
	s_ashr_i32 s43, s42, 31
	v_lshlrev_b64 v[6:7], 13, v[130:131]
	v_readlane_b32 s45, v253, 25
	v_lshl_add_u64 v[4:5], v[4:5], 0, s[2:3]
	s_lshl_b64 s[2:3], s[42:43], 13
	v_lshl_add_u64 v[6:7], s[44:45], 0, v[6:7]
	s_mov_b64 s[4:5], 0
	s_movk_i32 s8, 0x1fff
	v_lshlrev_b32_e32 v8, 2, v8
	v_mov_b32_e32 v9, v3
	s_movk_i32 s9, 0x1000
	s_movk_i32 s10, 0x2007
	v_readlane_b32 s46, v253, 26
	v_readlane_b32 s47, v253, 27
	v_readlane_b32 s48, v253, 28
	v_readlane_b32 s49, v253, 29
	v_readlane_b32 s50, v253, 30
	v_readlane_b32 s51, v253, 31
	v_readlane_b32 s52, v253, 32
	v_readlane_b32 s53, v253, 33
	v_readlane_b32 s54, v253, 34
	v_readlane_b32 s55, v253, 35
	v_readlane_b32 s56, v253, 36
	v_readlane_b32 s57, v253, 37
	v_readlane_b32 s58, v253, 38
	v_readlane_b32 s59, v253, 39
	s_branch .LBB0_118

.Lw1d_go:
	v_writelane_b32 v252, s12, 0
	v_writelane_b32 v252, s13, 1
	v_writelane_b32 v252, s14, 2
	v_writelane_b32 v252, s15, 3
	v_writelane_b32 v252, s17, 4
	v_writelane_b32 v252, s18, 5
	v_writelane_b32 v252, s19, 6
	v_writelane_b32 v252, s20, 7
	v_writelane_b32 v252, s21, 8
	v_writelane_b32 v252, s22, 9
	v_writelane_b32 v252, s24, 10
	v_writelane_b32 v252, s25, 11
	v_writelane_b32 v252, s26, 12
	v_writelane_b32 v252, s28, 13
	v_writelane_b32 v252, s44, 14
	v_writelane_b32 v252, s45, 15
	v_writelane_b32 v252, s46, 16
	v_writelane_b32 v252, s47, 17
	v_writelane_b32 v252, s48, 18
	v_writelane_b32 v252, s51, 19
	v_writelane_b32 v252, s52, 20
	v_writelane_b32 v252, s54, 21
	v_mov_b32_e32 v178, v4
	v_mov_b32_e32 v179, v5
	v_mov_b32_e32 v180, v49
	v_mov_b32_e32 v181, v153
	v_mov_b32_e32 v182, v66
	v_mov_b32_e32 v183, v67
	v_mov_b32_e32 v184, v68
	v_mov_b32_e32 v185, v69
	v_mov_b32_e32 v186, v70
	v_mov_b32_e32 v187, v71
	v_mov_b32_e32 v188, v72
	v_mov_b32_e32 v189, v73
	v_mov_b32_e32 v190, v74
	v_mov_b32_e32 v191, v75
	v_mov_b32_e32 v192, v76
	v_mov_b32_e32 v193, v77
	v_mov_b32_e32 v194, v78
	v_mov_b32_e32 v195, v79
	v_mov_b32_e32 v196, v80
	v_mov_b32_e32 v197, v81
	v_mov_b32_e32 v198, v82
	v_mov_b32_e32 v199, v83
	v_mov_b32_e32 v200, v84
	v_mov_b32_e32 v201, v85
	v_mov_b32_e32 v203, v86
	v_mov_b32_e32 v204, v87
	v_mov_b32_e32 v205, v88
	v_mov_b32_e32 v206, v89
	v_mov_b32_e32 v207, v90
	v_mov_b32_e32 v208, v91
	v_mov_b32_e32 v209, v92
	v_mov_b32_e32 v210, v93
	v_mov_b32_e32 v211, v94
	v_mov_b32_e32 v212, v95
	v_mov_b32_e32 v213, v96
	v_mov_b32_e32 v214, v97
	v_mov_b32_e32 v215, v98
	v_mov_b32_e32 v216, v99
	v_mov_b32_e32 v217, v100
	v_mov_b32_e32 v218, v101
	v_mov_b32_e32 v219, v102
	v_mov_b32_e32 v220, v103
	v_mov_b32_e32 v221, v104
	v_mov_b32_e32 v222, v105
	v_mov_b32_e32 v223, v106
	v_mov_b32_e32 v224, v107
	v_mov_b32_e32 v225, v108
	v_mov_b32_e32 v226, v109
	v_mov_b32_e32 v227, v110
	v_mov_b32_e32 v228, v111
	v_mov_b32_e32 v229, v112
	v_mov_b32_e32 v230, v113
	v_mov_b32_e32 v231, v114
	v_mov_b32_e32 v232, v115
	v_mov_b32_e32 v233, v116
	v_mov_b32_e32 v234, v117
	v_mov_b32_e32 v235, v118
	v_mov_b32_e32 v236, v119
	v_mov_b32_e32 v237, v120
	v_mov_b32_e32 v238, v121
	v_mov_b32_e32 v239, v122
	v_mov_b32_e32 v240, v123
	v_mov_b32_e32 v241, v124
	v_mov_b32_e32 v242, v125
	v_mov_b32_e32 v243, v126
	v_mov_b32_e32 v244, v127
	v_mov_b32_e32 v245, v128
	v_mov_b32_e32 v246, v129
	s_mov_b32 s96, 1
	v_readlane_b32 s0, v253, 21
	v_readlane_b32 s1, v253, 22
	v_readlane_b32 s98, v253, 0
	s_nop 3
	s_sub_u32 s0, s0, 0xe0
	s_subb_u32 s1, s1, 0
	v_readlane_b32 s99, v253, 23
	s_nop 3
	s_lshl_b32 s42, s99, 3
	s_mov_b32 s3, s98
	s_cmpk_lg_u32 s99, 0x100
	s_cbranch_scc1 .Lwt_any
	s_sub_u32 s3, s98, 0xac
	s_movk_i32 s42, 0x2a0
.Lwt_any:
	s_lshl_b32 s3, s3, 3
	s_add_u32 s3, s3, 0x3600
	v_mov_b32_e32 v139, v0
	v_ashrrev_i32_e32 v2, 6, v139
	v_and_b32_e32 v131, 63, v139
	v_and_b32_e32 v133, 15, v139
	v_add_u32_e32 v130, s3, v2
	s_add_u32 s20, s86, 0x4360200
	s_addc_u32 s21, s87, 0
	s_mov_b64 s[24:25], exec
	s_branch .Lpro_body
.Lpro_ret:
	s_mov_b32 s96, 0
	s_mov_b64 exec, -1
	v_mov_b32_e32 v4, v178
	v_mov_b32_e32 v5, v179
	v_mov_b32_e32 v49, v180
	v_mov_b32_e32 v153, v181
	v_mov_b32_e32 v66, v182
	v_mov_b32_e32 v67, v183
	v_mov_b32_e32 v68, v184
	v_mov_b32_e32 v69, v185
	v_mov_b32_e32 v70, v186
	v_mov_b32_e32 v71, v187
	v_mov_b32_e32 v72, v188
	v_mov_b32_e32 v73, v189
	v_mov_b32_e32 v74, v190
	v_mov_b32_e32 v75, v191
	v_mov_b32_e32 v76, v192
	v_mov_b32_e32 v77, v193
	v_mov_b32_e32 v78, v194
	v_mov_b32_e32 v79, v195
	v_mov_b32_e32 v80, v196
	v_mov_b32_e32 v81, v197
	v_mov_b32_e32 v82, v198
	v_mov_b32_e32 v83, v199
	v_mov_b32_e32 v84, v200
	v_mov_b32_e32 v85, v201
	v_mov_b32_e32 v86, v203
	v_mov_b32_e32 v87, v204
	v_mov_b32_e32 v88, v205
	v_mov_b32_e32 v89, v206
	v_mov_b32_e32 v90, v207
	v_mov_b32_e32 v91, v208
	v_mov_b32_e32 v92, v209
	v_mov_b32_e32 v93, v210
	v_mov_b32_e32 v94, v211
	v_mov_b32_e32 v95, v212
	v_mov_b32_e32 v96, v213
	v_mov_b32_e32 v97, v214
	v_mov_b32_e32 v98, v215
	v_mov_b32_e32 v99, v216
	v_mov_b32_e32 v100, v217
	v_mov_b32_e32 v101, v218
	v_mov_b32_e32 v102, v219
	v_mov_b32_e32 v103, v220
	v_mov_b32_e32 v104, v221
	v_mov_b32_e32 v105, v222
	v_mov_b32_e32 v106, v223
	v_mov_b32_e32 v107, v224
	v_mov_b32_e32 v108, v225
	v_mov_b32_e32 v109, v226
	v_mov_b32_e32 v110, v227
	v_mov_b32_e32 v111, v228
	v_mov_b32_e32 v112, v229
	v_mov_b32_e32 v113, v230
	v_mov_b32_e32 v114, v231
	v_mov_b32_e32 v115, v232
	v_mov_b32_e32 v116, v233
	v_mov_b32_e32 v117, v234
	v_mov_b32_e32 v118, v235
	v_mov_b32_e32 v119, v236
	v_mov_b32_e32 v120, v237
	v_mov_b32_e32 v121, v238
	v_mov_b32_e32 v122, v239
	v_mov_b32_e32 v123, v240
	v_mov_b32_e32 v124, v241
	v_mov_b32_e32 v125, v242
	v_mov_b32_e32 v126, v243
	v_mov_b32_e32 v127, v244
	v_mov_b32_e32 v128, v245
	v_mov_b32_e32 v129, v246
	v_readlane_b32 s12, v252, 0
	v_readlane_b32 s13, v252, 1
	v_readlane_b32 s14, v252, 2
	v_readlane_b32 s15, v252, 3
	v_readlane_b32 s17, v252, 4
	v_readlane_b32 s18, v252, 5
	v_readlane_b32 s19, v252, 6
	v_readlane_b32 s20, v252, 7
	v_readlane_b32 s21, v252, 8
	v_readlane_b32 s22, v252, 9
	v_readlane_b32 s24, v252, 10
	v_readlane_b32 s25, v252, 11
	v_readlane_b32 s26, v252, 12
	v_readlane_b32 s28, v252, 13
	v_readlane_b32 s44, v252, 14
	v_readlane_b32 s45, v252, 15
	v_readlane_b32 s46, v252, 16
	v_readlane_b32 s47, v252, 17
	v_readlane_b32 s48, v252, 18
	v_readlane_b32 s51, v252, 19
	v_readlane_b32 s52, v252, 20
	v_readlane_b32 s54, v252, 21
	s_nop 3
	v_readlane_b32 s0, v253, 21
	v_readlane_b32 s1, v253, 22
	s_nop 3
	s_sub_u32 s0, s0, 0xe0
	s_subb_u32 s1, s1, 0
	s_load_dwordx2 s[8:9], s[0:1], 0x50
	s_add_u32 s6, s86, 0xc600
	s_addc_u32 s7, s87, 0
	v_and_b32_e32 v6, 15, v0
	v_and_b32_e32 v7, 48, v0
	v_lshlrev_b32_e32 v8, 13, v7
	v_lshl_or_b32 v8, v6, 4, v8
	v_lshlrev_b32_e32 v9, 2, v6
	v_and_b32_e32 v9, 32, v9
	v_lshlrev_b32_e32 v10, 4, v6
	v_and_b32_e32 v10, 16, v10
	v_lshlrev_b32_e32 v11, 1, v6
	v_and_b32_e32 v11, 12, v11
	v_or3_b32 v9, v9, v10, v11
	v_mul_u32_u24_e32 v9, 0x2c00, v9
	v_lshl_add_u32 v12, v7, 1, v9
	v_add_u32_e32 v13, 0x2c00, v12
	v_add_u32_e32 v14, 0x5800, v12
	v_add_u32_e32 v15, 0x8400, v12
	v_mov_b32_e32 v16, 0
	v_mov_b32_e32 v17, 1
	s_mov_b64 exec, 1
	global_atomic_add v18, v16, v17, s[6:7] sc0
	s_mov_b64 exec, -1
	s_waitcnt vmcnt(0) lgkmcnt(0)
